# dead M0 save/restore pairs around the LDS-DMA pieces of the attention, chain and output units removed (24 pairs, inside the per-tile loops)
# baseline (speedup 1.0000x reference)
.LBB0_646:
	s_cmpk_gt_i32 s58, 0x47
	s_cselect_b64 s[52:53], -1, 0
	s_mov_b64 s[4:5], s[0:1]
	s_and_b64 vcc, exec, s[52:53]
	s_cbranch_vccnz .LBB0_642
	s_load_dwordx2 s[4:5], s[4:5], 0xa8
	s_lshl_b32 s6, s31, 2
	s_waitcnt lgkmcnt(0)
	s_add_u32 s4, s4, s6
	s_addc_u32 s5, s5, 0
	s_add_u32 s54, s4, 0x10000
	s_addc_u32 s55, s5, 0
	s_cmp_gt_i32 s58, 7
	s_mov_b64 s[4:5], -1
	s_cbranch_scc0 .LBB0_661
	s_mov_b64 s[8:9], s[0:1]
	s_load_dwordx2 s[4:5], s[8:9], 0xa8
	s_add_i32 s10, s58, -8
	v_mov_b32_e32 v146, v244
	s_load_dwordx2 s[8:9], s[8:9], 0x58
	s_waitcnt lgkmcnt(0)
	s_add_u32 s6, s4, 0x5800000
	s_addc_u32 s7, s5, 0
	s_lshl_b32 s11, s10, 7
	s_and_b32 s11, s11, 0x780
	v_ashrrev_i32_e32 v24, 3, v146
	v_lshrrev_b32_e32 v19, 4, v146
	s_or_b32 s59, s11, s90
	v_add_u32_e32 v16, s65, v24
	v_xor_b32_e32 v19, v19, v146
	s_add_u32 s11, s4, s95
	v_add_u32_e32 v18, 8, v16
	v_lshlrev_b32_e32 v19, 3, v19
	s_addc_u32 s12, s5, 0
	s_lshl_b32 s10, s10, 3
	v_and_b32_e32 v26, 56, v19
	v_ashrrev_i32_e32 v19, 31, v18
	s_and_b32 s60, s10, 0x7fffff80
	v_lshlrev_b64 v[20:21], 10, v[18:19]
	v_lshrrev_b32_e32 v18, 1, v18
	s_lshl_b32 s34, s60, 1
	v_xor_b32_e32 v18, v18, v146
	s_add_u32 s16, s11, s34
	v_lshlrev_b32_e32 v18, 3, v18
	s_addc_u32 s17, s12, 0
	v_and_b32_e32 v30, 56, v18
	v_add_u32_e32 v18, s64, v24
	s_add_u32 s12, s16, 0x7800000
	v_ashrrev_i32_e32 v17, 31, v16
	v_add_u32_e32 v31, 8, v18
	s_addc_u32 s13, s17, 0
	s_add_i32 s10, s51, s60
	v_lshlrev_b64 v[16:17], 10, v[16:17]
	v_lshrrev_b32_e32 v27, 1, v31
	v_or_b32_e32 v29, s66, v26
	s_mulk_i32 s10, 0x900
	s_mov_b32 s11, s35
	v_xor_b32_e32 v27, v27, v146
	v_lshl_add_u32 v156, v29, 1, v16
	v_or_b32_e32 v29, s66, v30
	v_and_b32_e32 v152, 31, v146
	s_lshl_b64 s[10:11], s[10:11], 1
	v_lshl_add_u64 v[22:23], s[12:13], 0, v[20:21]
	v_lshl_add_u32 v154, v29, 1, v20
	v_lshlrev_b32_e32 v20, 4, v27
	s_add_u32 s14, s4, s10
	v_mul_lo_u32 v21, v18, s30
	v_lshlrev_b32_e32 v144, 1, v26
	v_and_b32_e32 v26, 0x70, v20
	v_or_b32_e32 v20, s59, v152
	s_addc_u32 s15, s5, s11
	v_or_b32_e32 v150, v144, v21
	v_lshlrev_b32_e32 v20, 11, v20
	v_mov_b32_e32 v21, v145
	v_ashrrev_i32_e32 v153, 5, v146
	s_add_u32 s10, s14, 0x8a00000
	v_mul_lo_u32 v28, v31, s30
	v_lshl_add_u64 v[20:21], s[6:7], 0, v[20:21]
	s_addc_u32 s11, s15, 0
	v_or_b32_e32 v148, v26, v28
	v_lshl_add_u64 v[20:21], v[20:21], 0, s[34:35]
	s_lshl_b32 s34, s66, 1
	v_lshlrev_b32_e32 v28, 3, v153
	v_lshl_add_u64 v[20:21], v[20:21], 0, s[34:35]
	v_ashrrev_i32_e32 v29, 31, v28
	v_lshl_add_u64 v[28:29], v[28:29], 1, v[20:21]
	global_load_dwordx4 v[124:127], v[28:29], off
	global_load_dwordx4 v[120:123], v[28:29], off offset:32
	global_load_dwordx4 v[116:119], v[28:29], off offset:64
	global_load_dwordx4 v[112:115], v[28:29], off offset:96
	v_lshl_add_u64 v[16:17], s[12:13], 0, v[16:17]
	v_lshl_add_u64 v[16:17], v[16:17], 0, s[34:35]
	v_mov_b64_e32 v[24:25], s[10:11]
	v_lshl_add_u64 v[20:21], v[16:17], 0, v[144:145]
	v_lshl_add_u64 v[16:17], v[22:23], 0, s[34:35]
	v_lshlrev_b32_e32 v22, 1, v30
	v_mov_b32_e32 v23, v145
	v_mad_i64_i32 v[18:19], s[18:19], v18, s30, v[24:25]
	v_mov_b32_e32 v27, v145
	v_lshl_add_u64 v[22:23], v[16:17], 0, v[22:23]
	v_mad_i64_i32 v[16:17], s[18:19], v31, s30, v[24:25]
	s_mov_b32 s61, 1
	v_lshl_add_u64 v[18:19], v[18:19], 0, v[144:145]
	v_lshl_add_u64 v[16:17], v[16:17], 0, v[26:27]
	v_lshlrev_b32_e32 v25, 1, v146
	v_lshrrev_b32_e32 v56, 1, v146
	s_mov_b32 m0, s67
	s_nop 0
	global_load_lds_dwordx4 v[20:21], off
	v_and_b32_e32 v24, 19, v146
	v_and_b32_e32 v25, 8, v25
	v_and_b32_e32 v26, 4, v56
	s_add_i32 s18, s67, 0x400
	s_mov_b32 m0, s18
	s_nop 0
	global_load_lds_dwordx4 v[22:23], off
	v_or3_b32 v24, v25, v24, v26
	s_mov_b32 m0, s70
	s_nop 0
	global_load_lds_dwordx4 v[18:19], off
	v_lshrrev_b32_e32 v58, 1, v24
	s_add_i32 s18, s67, 0x4400
	s_mov_b32 m0, s18
	s_nop 0
	global_load_lds_dwordx4 v[16:17], off
	v_lshl_or_b32 v57, v24, 7, s68
	v_bitop3_b32 v24, v58, v153, 7 bitop3:0x6c
	v_lshl_add_u32 v144, v24, 4, v57
	s_waitcnt vmcnt(0) lgkmcnt(0)
	s_barrier
	s_waitcnt vmcnt(3)
	s_waitcnt vmcnt(2)
	s_waitcnt vmcnt(1)
	s_waitcnt vmcnt(0)
	v_lshl_add_u64 v[24:25], v[20:21], 0, s[36:37]
	s_mov_b32 m0, s71
	s_nop 0
	global_load_lds_dwordx4 v[24:25], off
	v_lshl_add_u64 v[24:25], v[22:23], 0, s[36:37]
	s_mov_b32 m0, s72
	s_nop 0
	global_load_lds_dwordx4 v[24:25], off
	v_lshl_add_u64 v[24:25], v[18:19], 0, s[38:39]
	s_mov_b32 m0, s73
	s_nop 0
	global_load_lds_dwordx4 v[24:25], off
	v_lshl_add_u64 v[24:25], v[16:17], 0, s[38:39]
	s_mov_b32 m0, s78
	s_nop 0
	global_load_lds_dwordx4 v[24:25], off
	v_lshl_add_u64 v[20:21], v[20:21], 0, s[40:41]
	s_add_i32 s18, s67, 0x10000
	s_mov_b32 m0, s18
	s_nop 0
	global_load_lds_dwordx4 v[20:21], off
	v_lshl_add_u64 v[20:21], v[22:23], 0, s[40:41]
	s_add_i32 s18, s67, 0x10400
	s_mov_b32 m0, s18
	s_nop 0
	global_load_lds_dwordx4 v[20:21], off
	v_lshl_add_u64 v[18:19], v[18:19], 0, s[42:43]
	s_add_i32 s18, s67, 0x14000
	s_mov_b32 m0, s18
	s_nop 0
	global_load_lds_dwordx4 v[18:19], off
	v_lshl_add_u64 v[16:17], v[16:17], 0, s[42:43]
	s_add_i32 s18, s67, 0x14400
	s_mov_b32 m0, s18
	s_nop 0
	global_load_lds_dwordx4 v[16:17], off
	v_add_u32_e32 v16, 0, v144
	ds_read_b128 v[32:35], v16
	ds_read_b128 v[48:51], v16 offset:4096
	s_waitcnt lgkmcnt(1)
	v_mfma_f32_32x32x16_bf16 v[16:31], v[32:35], v[124:127], v[0:15]
	v_add_u32_e32 v59, 2, v153
	v_bitop3_b32 v32, v58, v59, 7 bitop3:0x6c
	v_lshl_add_u32 v157, v32, 4, v57
	v_add_u32_e32 v52, 0, v157
	v_add_u32_e32 v60, 4, v153
	v_add_u32_e32 v61, 6, v153
	s_add_u32 s14, s14, 0x8a00180
	s_waitcnt lgkmcnt(0)
	v_mfma_f32_32x32x16_bf16 v[32:47], v[48:51], v[124:127], v[0:15]
	ds_read_b128 v[48:51], v52
	ds_read_b128 v[52:55], v52 offset:4096
	s_addc_u32 s15, s15, 0
	v_lshlrev_b32_e32 v166, 7, v152
	s_add_u32 s16, s16, 0x7830000
	v_mov_b32_e32 v158, 0
	s_addc_u32 s17, s17, 0
	s_movk_i32 s96, 0x100
	s_waitcnt lgkmcnt(1)
	v_mfma_f32_32x32x16_bf16 v[16:31], v[48:51], v[120:123], v[16:31]
	v_bitop3_b32 v48, v58, v60, 7 bitop3:0x6c
	v_lshl_add_u32 v159, v48, 4, v57
	s_mov_b32 s97, 0x20000
	v_mov_b32_e32 v62, v158
	v_mov_b32_e32 v63, v158
	v_mov_b32_e32 v64, 0
	v_mov_b32_e32 v65, v158
	s_waitcnt lgkmcnt(0)
	v_mfma_f32_32x32x16_bf16 v[32:47], v[52:55], v[120:123], v[32:47]
	v_add_u32_e32 v52, 0, v159
	ds_read_b128 v[48:51], v52
	ds_read_b128 v[52:55], v52 offset:4096
	v_mov_b32_e32 v66, v158
	v_mov_b32_e32 v67, v158
	v_mov_b32_e32 v68, v158
	v_mov_b32_e32 v69, v158
	v_mov_b32_e32 v70, v158
	s_waitcnt lgkmcnt(1)
	v_mfma_f32_32x32x16_bf16 v[16:31], v[48:51], v[116:119], v[16:31]
	v_bitop3_b32 v48, v58, v61, 7 bitop3:0x6c
	v_lshl_add_u32 v160, v48, 4, v57
	v_bitop3_b32 v57, v56, v153, 7 bitop3:0x6c
	v_lshlrev_b32_e32 v162, 4, v57
	v_add_u32_e32 v167, v162, v166
	v_mov_b32_e32 v57, v158
	v_mov_b32_e32 v58, v158
	s_waitcnt lgkmcnt(0)
	v_mfma_f32_32x32x16_bf16 v[32:47], v[52:55], v[116:119], v[32:47]
	v_add_u32_e32 v52, 0, v160
	ds_read_b128 v[48:51], v52
	ds_read_b128 v[52:55], v52 offset:4096
	v_mov_b32_e32 v71, v158
	v_mov_b32_e32 v72, v158
	v_mov_b32_e32 v73, v158
	v_mov_b32_e32 v74, v158
	s_waitcnt lgkmcnt(1)
	v_mfma_f32_32x32x16_bf16 v[16:31], v[48:51], v[112:115], v[16:31]
	v_bitop3_b32 v48, v59, v56, 7 bitop3:0x78
	v_lshlrev_b32_e32 v163, 4, v48
	v_bitop3_b32 v48, v60, v56, 7 bitop3:0x78
	v_lshlrev_b32_e32 v164, 4, v48
	v_bitop3_b32 v48, v61, v56, 7 bitop3:0x78
	v_lshlrev_b32_e32 v165, 4, v48
	v_add_u32_e32 v168, v163, v166
	s_waitcnt lgkmcnt(0)
	v_mfma_f32_32x32x16_bf16 v[32:47], v[52:55], v[112:115], v[32:47]
	s_nop 2
	v_exp_f32_e32 v194, v16
	v_exp_f32_e32 v195, v17
	v_exp_f32_e32 v196, v18
	v_exp_f32_e32 v197, v19
	v_exp_f32_e32 v198, v20
	v_exp_f32_e32 v200, v21
	v_exp_f32_e32 v199, v22
	s_nop 1
	v_exp_f32_e32 v173, v32
	v_exp_f32_e32 v174, v33
	v_exp_f32_e32 v175, v34
	v_exp_f32_e32 v176, v35
	v_exp_f32_e32 v191, v36
	v_exp_f32_e32 v188, v37
	v_exp_f32_e32 v171, v38
	v_exp_f32_e32 v201, v23
	v_exp_f32_e32 v172, v39
	v_exp_f32_e32 v180, v24
	v_exp_f32_e32 v185, v40
	v_exp_f32_e32 v181, v25
	v_exp_f32_e32 v186, v41
	v_exp_f32_e32 v182, v26
	v_exp_f32_e32 v187, v42
	v_exp_f32_e32 v183, v27
	v_exp_f32_e32 v184, v43
	v_exp_f32_e32 v193, v28
	v_exp_f32_e32 v177, v44
	v_exp_f32_e32 v189, v29
	v_exp_f32_e32 v178, v45
	v_exp_f32_e32 v190, v30
	v_exp_f32_e32 v179, v46
	v_exp_f32_e32 v192, v31
	v_exp_f32_e32 v161, v47
	v_add_u32_e32 v169, v164, v166
	v_add_u32_e32 v170, v165, v166
	v_mov_b32_e32 v16, 0
	v_mov_b32_e32 v17, v158
	v_mov_b32_e32 v18, v158
	v_mov_b32_e32 v19, v158
	v_mov_b32_e32 v20, v158
	v_mov_b32_e32 v21, v158
	v_mov_b32_e32 v22, v158
	v_mov_b32_e32 v23, v158
	v_mov_b32_e32 v24, v158
	v_mov_b32_e32 v25, v158
	v_mov_b32_e32 v26, v158
	v_mov_b32_e32 v27, v158
	v_mov_b32_e32 v28, v158
	v_mov_b32_e32 v29, v158
	v_mov_b32_e32 v30, v158
	v_mov_b32_e32 v31, v158
	v_mov_b32_e32 v32, 0
	v_mov_b32_e32 v33, v158
	v_mov_b32_e32 v34, v158
	v_mov_b32_e32 v35, v158
	v_mov_b32_e32 v36, v158
	v_mov_b32_e32 v37, v158
	v_mov_b32_e32 v38, v158
	v_mov_b32_e32 v39, v158
	v_mov_b32_e32 v40, v158
	v_mov_b32_e32 v41, v158
	v_mov_b32_e32 v42, v158
	v_mov_b32_e32 v43, v158
	v_mov_b32_e32 v44, v158
	v_mov_b32_e32 v45, v158
	v_mov_b32_e32 v46, v158
	v_mov_b32_e32 v47, v158
	v_mov_b32_e32 v48, 0
	v_mov_b32_e32 v49, v158
	v_mov_b32_e32 v50, v158
	v_mov_b32_e32 v51, v158
	v_mov_b32_e32 v52, v158
	v_mov_b32_e32 v53, v158
	v_mov_b32_e32 v54, v158
	v_mov_b32_e32 v55, v158
	v_mov_b32_e32 v56, v158
	v_mov_b32_e32 v59, v158
	v_mov_b32_e32 v60, v158
	v_mov_b32_e32 v61, v158
	v_mov_b32_e32 v75, v158
	v_mov_b32_e32 v76, v158
	v_mov_b32_e32 v77, v158
	v_mov_b32_e32 v78, v158
	v_mov_b32_e32 v79, v158
.LBB0_649:
	s_add_i32 s18, s97, 0xfffe8000
	s_and_b32 s18, s18, 0x18000
	s_add_i32 vcc_hi, s18, 0
	s_waitcnt vmcnt(4) lgkmcnt(0)
	s_barrier
	v_add_u32_e32 v132, vcc_hi, v144
	v_add_u32_e32 v136, vcc_hi, v159
	v_add_u32_e32 v133, vcc_hi, v157
	ds_read_b128 v[96:99], v132
	ds_read_b128 v[100:103], v133
	v_add_u32_e32 v137, vcc_hi, v160
	ds_read_b128 v[104:107], v136
	ds_read_b128 v[108:111], v137
	s_and_b32 s26, s97, 0x18000
	s_add_i32 vcc_lo, s61, 2
	s_add_i32 s18, s26, 0
	ds_read_b128 v[202:205], v132 offset:4096
	ds_read_b128 v[206:209], v133 offset:4096
	s_waitcnt lgkmcnt(5)
	v_mfma_f32_32x32x16_bf16 v[80:95], v[96:99], v[124:127], v[0:15]
	v_cvt_pk_bf16_f32 v128, v194, v195
	v_cvt_pk_bf16_f32 v129, v196, v197
	v_cvt_pk_bf16_f32 v130, v198, v200
	v_cvt_pk_bf16_f32 v131, v199, v201
	ds_read_b128 v[210:213], v136 offset:4096
	ds_read_b128 v[214:217], v137 offset:4096
	s_waitcnt lgkmcnt(6)
	v_mfma_f32_32x32x16_bf16 v[80:95], v[100:103], v[120:123], v[80:95]
	v_cvt_pk_bf16_f32 v132, v180, v181
	v_cvt_pk_bf16_f32 v133, v182, v183
	v_cvt_pk_bf16_f32 v134, v193, v189
	v_cvt_pk_bf16_f32 v135, v190, v192
	v_add_u32_e32 v234, s18, v167
	v_add_u32_e32 v235, s18, v168
	ds_read_b128 v[218:221], v234 offset:16384
	ds_read_b128 v[222:225], v235 offset:16384
	s_waitcnt lgkmcnt(7)
	v_mfma_f32_32x32x16_bf16 v[80:95], v[104:107], v[116:119], v[80:95]
	v_cvt_pk_bf16_f32 v136, v173, v174
	v_cvt_pk_bf16_f32 v137, v175, v176
	v_cvt_pk_bf16_f32 v138, v191, v188
	v_cvt_pk_bf16_f32 v139, v171, v172
	v_add_u32_e32 v236, s18, v169
	v_add_u32_e32 v237, s18, v170
	ds_read_b128 v[226:229], v236 offset:16384
	ds_read_b128 v[230:233], v237 offset:16384
	s_waitcnt lgkmcnt(8)
	v_mfma_f32_32x32x16_bf16 v[80:95], v[108:111], v[112:115], v[80:95]
	v_cvt_pk_bf16_f32 v140, v185, v186
	v_cvt_pk_bf16_f32 v141, v187, v184
	v_cvt_pk_bf16_f32 v142, v177, v178
	v_cvt_pk_bf16_f32 v143, v179, v161
	v_add_f32_e32 v96, 0, v194
	v_add_f32_e32 v96, v195, v96
	v_add_f32_e32 v96, v196, v96
	v_add_f32_e32 v96, v197, v96
	v_add_f32_e32 v96, v198, v96
	v_add_f32_e32 v194, v200, v96
	v_add_f32_e32 v194, v199, v194
	v_add_f32_e32 v194, v201, v194
	s_waitcnt lgkmcnt(7)
	v_mfma_f32_32x32x16_bf16 v[96:111], v[202:205], v[124:127], v[0:15]
	v_exp_f32_e32 v195, v80
	v_exp_f32_e32 v196, v81
	v_exp_f32_e32 v197, v82
	v_exp_f32_e32 v198, v83
	s_waitcnt lgkmcnt(6)
	v_mfma_f32_32x32x16_bf16 v[96:111], v[206:209], v[120:123], v[96:111]
	v_exp_f32_e32 v199, v84
	v_exp_f32_e32 v200, v85
	v_exp_f32_e32 v201, v86
	s_waitcnt lgkmcnt(5)
	v_mfma_f32_32x32x16_bf16 v[96:111], v[210:213], v[116:119], v[96:111]
	v_exp_f32_e32 v238, v87
	s_waitcnt lgkmcnt(4)
	v_mfma_f32_32x32x16_bf16 v[96:111], v[214:217], v[112:115], v[96:111]
	v_exp_f32_e32 v214, v88
	v_exp_f32_e32 v215, v89
	v_exp_f32_e32 v216, v90
	v_exp_f32_e32 v217, v91
	s_waitcnt lgkmcnt(3)
	v_mfma_f32_32x32x16_bf16 v[64:79], v[128:131], v[218:221], v[64:79]
	ds_read_b128 v[80:83], v234 offset:20480
	v_exp_f32_e32 v218, v92
	v_exp_f32_e32 v219, v93
	v_exp_f32_e32 v220, v94
	v_exp_f32_e32 v221, v95
	s_waitcnt lgkmcnt(3)
	v_mfma_f32_32x32x16_bf16 v[64:79], v[132:135], v[222:225], v[64:79]
	v_add_f32_e32 v88, v180, v194
	v_add_f32_e32 v88, v181, v88
	v_add_f32_e32 v88, v182, v88
	v_add_f32_e32 v88, v183, v88
	ds_read_b128 v[84:87], v235 offset:20480
	v_add_f32_e32 v88, v193, v88
	v_add_f32_e32 v88, v189, v88
	v_add_f32_e32 v88, v190, v88
	v_add_f32_e32 v180, v192, v88
	s_waitcnt lgkmcnt(3)
	v_mfma_f32_32x32x16_bf16 v[64:79], v[136:139], v[226:229], v[64:79]
	ds_read_b128 v[88:91], v236 offset:20480
	v_exp_f32_e32 v222, v96
	v_exp_f32_e32 v223, v97
	v_exp_f32_e32 v224, v98
	v_exp_f32_e32 v225, v99
	s_waitcnt lgkmcnt(3)
	v_mfma_f32_32x32x16_bf16 v[64:79], v[140:143], v[230:233], v[64:79]
	v_add_f32_e32 v96, v173, v180
	ds_read_b128 v[92:95], v237 offset:20480
	v_add_f32_e32 v96, v174, v96
	v_add_f32_e32 v96, v175, v96
	v_add_f32_e32 v96, v176, v96
	v_add_f32_e32 v96, v191, v96
	v_add_f32_e32 v96, v188, v96
	s_waitcnt lgkmcnt(3)
	v_mfma_f32_32x32x16_bf16 v[48:63], v[128:131], v[80:83], v[48:63]
	ds_read_b128 v[80:83], v234 offset:24576
	v_exp_f32_e32 v226, v100
	v_exp_f32_e32 v227, v101
	v_exp_f32_e32 v228, v102
	v_exp_f32_e32 v229, v103
	s_waitcnt lgkmcnt(3)
	v_mfma_f32_32x32x16_bf16 v[48:63], v[132:135], v[84:87], v[48:63]
	v_add_f32_e32 v96, v171, v96
	ds_read_b128 v[84:87], v235 offset:24576
	v_add_f32_e32 v96, v172, v96
	v_add_f32_e32 v96, v185, v96
	v_add_f32_e32 v96, v186, v96
	v_add_f32_e32 v96, v187, v96
	v_add_f32_e32 v96, v184, v96
	s_waitcnt lgkmcnt(3)
	v_mfma_f32_32x32x16_bf16 v[48:63], v[136:139], v[88:91], v[48:63]
	ds_read_b128 v[88:91], v236 offset:24576
	v_exp_f32_e32 v230, v104
	v_exp_f32_e32 v231, v105
	v_exp_f32_e32 v232, v106
	v_exp_f32_e32 v233, v107
	s_waitcnt lgkmcnt(3)
	v_mfma_f32_32x32x16_bf16 v[48:63], v[140:143], v[92:95], v[48:63]
	ds_read_b128 v[92:95], v237 offset:24576
	v_add_f32_e32 v96, v177, v96
	v_add_f32_e32 v96, v178, v96
	v_add_f32_e32 v96, v179, v96
	v_add_f32_e32 v96, v161, v96
	s_waitcnt lgkmcnt(3)
	v_mfma_f32_32x32x16_bf16 v[32:47], v[128:131], v[80:83], v[32:47]
	ds_read_b128 v[80:83], v234 offset:28672
	v_exp_f32_e32 v161, v108
	v_exp_f32_e32 v234, v109
	v_exp_f32_e32 v239, v110
	v_exp_f32_e32 v240, v111
	s_waitcnt lgkmcnt(3)
	v_mfma_f32_32x32x16_bf16 v[32:47], v[132:135], v[84:87], v[32:47]
	ds_read_b128 v[84:87], v235 offset:28672
	s_waitcnt lgkmcnt(3)
	v_mfma_f32_32x32x16_bf16 v[32:47], v[136:139], v[88:91], v[32:47]
	ds_read_b128 v[88:91], v236 offset:28672
	s_waitcnt lgkmcnt(3)
	v_mfma_f32_32x32x16_bf16 v[32:47], v[140:143], v[92:95], v[32:47]
	ds_read_b128 v[92:95], v237 offset:28672
	s_waitcnt lgkmcnt(3)
	v_mfma_f32_32x32x16_bf16 v[16:31], v[128:131], v[80:83], v[16:31]
	s_add_i32 s18, s97, 0xffff8000
	s_and_b32 s18, s18, 0x18000
	s_add_i32 s19, s18, s67
	s_mov_b32 m0, s19
	s_nop 0
	global_load_lds_dwordx4 v156, s[16:17]
	s_waitcnt lgkmcnt(2)
	v_mfma_f32_32x32x16_bf16 v[16:31], v[132:135], v[84:87], v[16:31]
	s_addk_i32 s19, 0x400
	s_mov_b32 m0, s19
	s_nop 0
	global_load_lds_dwordx4 v154, s[16:17]
	s_waitcnt lgkmcnt(1)
	v_mfma_f32_32x32x16_bf16 v[16:31], v[136:139], v[88:91], v[16:31]
	s_add_i32 s18, s18, s70
	s_mov_b32 m0, s18
	s_nop 0
	global_load_lds_dwordx4 v150, s[14:15]
	s_waitcnt lgkmcnt(0)
	v_mfma_f32_32x32x16_bf16 v[16:31], v[140:143], v[92:95], v[16:31]
	s_addk_i32 s18, 0x400
	s_mov_b32 m0, s18
	s_nop 0
	global_load_lds_dwordx4 v148, s[14:15]
	s_add_i32 s18, s97, 0xffff0000
	s_and_b32 s18, s18, 0x18000
	s_add_i32 s18, s18, 0
	s_cmp_lt_u32 s61, 33
	s_cselect_b32 s34, s96, 0x8c0
	v_add_u32_e32 v132, s18, v144
	v_add_u32_e32 v133, s18, v157
	v_add_u32_e32 v136, s18, v159
	v_add_u32_e32 v137, s18, v160
	s_lshl_b64 s[18:19], s[34:35], 10
	s_add_u32 s56, s12, s18
	s_addc_u32 s57, s13, s19
	s_add_i32 s77, s26, s67
	s_waitcnt vmcnt(4) lgkmcnt(0)
	s_barrier
	s_lshl_b64 s[18:19], s[34:35], 1
	s_add_i32 s34, s77, 0x400
	v_add_f32_e32 v158, v158, v96
	ds_read_b128 v[96:99], v132
	ds_read_b128 v[100:103], v133
	ds_read_b128 v[104:107], v136
	ds_read_b128 v[108:111], v137
	s_add_u32 s18, s10, s18
	s_addc_u32 s19, s11, s19
	s_add_i32 s27, s26, s70
	s_addk_i32 s96, 0x80
	s_add_i32 s97, s97, 0x10000
	s_add_i32 s26, s27, 0x400
	s_add_u32 s14, s14, 0x100
	s_addc_u32 s15, s15, 0
	s_add_u32 s16, s16, 0x20000
	s_addc_u32 s17, s17, 0
	s_cmp_gt_u32 s61, 32
	ds_read_b128 v[172:175], v132 offset:4096
	ds_read_b128 v[176:179], v133 offset:4096
	s_waitcnt lgkmcnt(5)
	v_mfma_f32_32x32x16_bf16 v[80:95], v[96:99], v[124:127], v[0:15]
	v_cvt_pk_bf16_f32 v128, v195, v196
	v_cvt_pk_bf16_f32 v129, v197, v198
	v_cvt_pk_bf16_f32 v130, v199, v200
	v_cvt_pk_bf16_f32 v131, v201, v238
	ds_read_b128 v[180:183], v136 offset:4096
	ds_read_b128 v[184:187], v137 offset:4096
	s_waitcnt lgkmcnt(6)
	v_mfma_f32_32x32x16_bf16 v[80:95], v[100:103], v[120:123], v[80:95]
	v_cvt_pk_bf16_f32 v132, v214, v215
	v_cvt_pk_bf16_f32 v133, v216, v217
	v_cvt_pk_bf16_f32 v134, v218, v219
	v_cvt_pk_bf16_f32 v135, v220, v221
	v_add_u32_e32 v235, vcc_hi, v167
	ds_read_b128 v[188:191], v235 offset:16384
	v_add_u32_e32 v236, vcc_hi, v168
	ds_read_b128 v[202:205], v236 offset:16384
	s_waitcnt lgkmcnt(7)
	v_mfma_f32_32x32x16_bf16 v[80:95], v[104:107], v[116:119], v[80:95]
	v_cvt_pk_bf16_f32 v136, v222, v223
	v_cvt_pk_bf16_f32 v137, v224, v225
	v_cvt_pk_bf16_f32 v138, v226, v227
	v_cvt_pk_bf16_f32 v139, v228, v229
	v_add_u32_e32 v237, vcc_hi, v169
	v_add_u32_e32 v241, vcc_hi, v170
	ds_read_b128 v[206:209], v237 offset:16384
	ds_read_b128 v[210:213], v241 offset:16384
	s_waitcnt lgkmcnt(8)
	v_mfma_f32_32x32x16_bf16 v[80:95], v[108:111], v[112:115], v[80:95]
	v_cvt_pk_bf16_f32 v140, v230, v231
	v_cvt_pk_bf16_f32 v141, v232, v233
	v_cvt_pk_bf16_f32 v142, v161, v234
	v_cvt_pk_bf16_f32 v143, v239, v240
	v_add_f32_e32 v96, 0, v195
	v_add_f32_e32 v96, v196, v96
	v_add_f32_e32 v96, v197, v96
	v_add_f32_e32 v96, v198, v96
	v_add_f32_e32 v96, v199, v96
	v_add_f32_e32 v171, v200, v96
	v_add_f32_e32 v171, v201, v171
	v_add_f32_e32 v171, v238, v171
	s_waitcnt lgkmcnt(7)
	v_mfma_f32_32x32x16_bf16 v[96:111], v[172:175], v[124:127], v[0:15]
	v_exp_f32_e32 v194, v80
	v_exp_f32_e32 v195, v81
	v_exp_f32_e32 v196, v82
	v_exp_f32_e32 v197, v83
	s_waitcnt lgkmcnt(6)
	v_mfma_f32_32x32x16_bf16 v[96:111], v[176:179], v[120:123], v[96:111]
	v_exp_f32_e32 v198, v84
	v_exp_f32_e32 v200, v85
	v_exp_f32_e32 v199, v86
	v_exp_f32_e32 v201, v87
	s_waitcnt lgkmcnt(5)
	v_mfma_f32_32x32x16_bf16 v[96:111], v[180:183], v[116:119], v[96:111]
	v_exp_f32_e32 v180, v88
	v_exp_f32_e32 v181, v89
	v_exp_f32_e32 v182, v90
	v_exp_f32_e32 v183, v91
	s_waitcnt lgkmcnt(4)
	v_mfma_f32_32x32x16_bf16 v[96:111], v[184:187], v[112:115], v[96:111]
	s_waitcnt lgkmcnt(3)
	v_mfma_f32_32x32x16_bf16 v[64:79], v[128:131], v[188:191], v[64:79]
	ds_read_b128 v[80:83], v235 offset:20480
	v_exp_f32_e32 v193, v92
	v_exp_f32_e32 v189, v93
	v_exp_f32_e32 v190, v94
	v_exp_f32_e32 v192, v95
	s_waitcnt lgkmcnt(3)
	v_mfma_f32_32x32x16_bf16 v[64:79], v[132:135], v[202:205], v[64:79]
	v_add_f32_e32 v88, v214, v171
	v_add_f32_e32 v88, v215, v88
	v_add_f32_e32 v88, v216, v88
	v_add_f32_e32 v88, v217, v88
	ds_read_b128 v[84:87], v236 offset:20480
	v_add_f32_e32 v88, v218, v88
	v_add_f32_e32 v88, v219, v88
	v_add_f32_e32 v88, v220, v88
	v_add_f32_e32 v171, v221, v88
	s_waitcnt lgkmcnt(3)
	v_mfma_f32_32x32x16_bf16 v[64:79], v[136:139], v[206:209], v[64:79]
	ds_read_b128 v[88:91], v237 offset:20480
	v_exp_f32_e32 v173, v96
	v_exp_f32_e32 v174, v97
	v_exp_f32_e32 v175, v98
	v_exp_f32_e32 v176, v99
	s_waitcnt lgkmcnt(3)
	v_mfma_f32_32x32x16_bf16 v[64:79], v[140:143], v[210:213], v[64:79]
	v_add_f32_e32 v96, v222, v171
	ds_read_b128 v[92:95], v241 offset:20480
	v_add_f32_e32 v96, v223, v96
	v_add_f32_e32 v96, v224, v96
	v_add_f32_e32 v96, v225, v96
	v_add_f32_e32 v96, v226, v96
	v_add_f32_e32 v96, v227, v96
	s_waitcnt lgkmcnt(3)
	v_mfma_f32_32x32x16_bf16 v[48:63], v[128:131], v[80:83], v[48:63]
	ds_read_b128 v[80:83], v235 offset:24576
	v_exp_f32_e32 v191, v100
	v_exp_f32_e32 v188, v101
	v_exp_f32_e32 v171, v102
	v_exp_f32_e32 v172, v103
	s_waitcnt lgkmcnt(3)
	v_mfma_f32_32x32x16_bf16 v[48:63], v[132:135], v[84:87], v[48:63]
	v_add_f32_e32 v96, v228, v96
	ds_read_b128 v[84:87], v236 offset:24576
	v_add_f32_e32 v96, v229, v96
	v_add_f32_e32 v96, v230, v96
	v_add_f32_e32 v96, v231, v96
	v_add_f32_e32 v96, v232, v96
	v_add_f32_e32 v96, v233, v96
	s_waitcnt lgkmcnt(3)
	v_mfma_f32_32x32x16_bf16 v[48:63], v[136:139], v[88:91], v[48:63]
	ds_read_b128 v[88:91], v237 offset:24576
	v_exp_f32_e32 v185, v104
	v_exp_f32_e32 v186, v105
	v_exp_f32_e32 v187, v106
	v_exp_f32_e32 v184, v107
	s_waitcnt lgkmcnt(3)
	v_mfma_f32_32x32x16_bf16 v[48:63], v[140:143], v[92:95], v[48:63]
	ds_read_b128 v[92:95], v241 offset:24576
	v_add_f32_e32 v96, v161, v96
	v_add_f32_e32 v96, v234, v96
	v_add_f32_e32 v96, v239, v96
	v_add_f32_e32 v96, v240, v96
	s_waitcnt lgkmcnt(3)
	v_mfma_f32_32x32x16_bf16 v[32:47], v[128:131], v[80:83], v[32:47]
	ds_read_b128 v[80:83], v235 offset:28672
	v_exp_f32_e32 v177, v108
	v_exp_f32_e32 v178, v109
	v_exp_f32_e32 v179, v110
	v_exp_f32_e32 v161, v111
	s_waitcnt lgkmcnt(3)
	v_mfma_f32_32x32x16_bf16 v[32:47], v[132:135], v[84:87], v[32:47]
	ds_read_b128 v[84:87], v236 offset:28672
	s_waitcnt lgkmcnt(3)
	v_mfma_f32_32x32x16_bf16 v[32:47], v[136:139], v[88:91], v[32:47]
	ds_read_b128 v[88:91], v237 offset:28672
	s_waitcnt lgkmcnt(3)
	v_mfma_f32_32x32x16_bf16 v[32:47], v[140:143], v[92:95], v[32:47]
	ds_read_b128 v[92:95], v241 offset:28672
	s_waitcnt lgkmcnt(3)
	v_mfma_f32_32x32x16_bf16 v[16:31], v[128:131], v[80:83], v[16:31]
	s_mov_b32 m0, s77
	s_nop 0
	global_load_lds_dwordx4 v156, s[56:57]
	s_waitcnt lgkmcnt(2)
	v_mfma_f32_32x32x16_bf16 v[16:31], v[132:135], v[84:87], v[16:31]
	s_mov_b32 m0, s34
	s_nop 0
	global_load_lds_dwordx4 v154, s[56:57]
	s_waitcnt lgkmcnt(1)
	v_mfma_f32_32x32x16_bf16 v[16:31], v[136:139], v[88:91], v[16:31]
	s_mov_b32 m0, s27
	s_nop 0
	global_load_lds_dwordx4 v150, s[18:19]
	s_waitcnt lgkmcnt(0)
	v_mfma_f32_32x32x16_bf16 v[16:31], v[140:143], v[92:95], v[16:31]
	s_mov_b32 m0, s26
	s_nop 0
	global_load_lds_dwordx4 v148, s[18:19]
	v_add_f32_e32 v158, v158, v96
	s_mov_b32 s61, vcc_lo
	s_cbranch_scc0 .LBB0_649
	v_or_b32_e32 v80, s75, v146
	v_cmp_eq_u32_e32 vcc, 0, v80
	s_and_saveexec_b64 s[14:15], vcc
	s_cbranch_execz .LBB0_652
	v_mov_b64_e32 v[80:81], s[54:55]
	global_atomic_add v136, v[80:81], v147, off sc0
.LBB0_652:
	s_or_b64 exec, exec, s[14:15]
	s_add_i32 s14, 0, 0x18000
	s_waitcnt vmcnt(4) lgkmcnt(0)
	s_barrier
	v_add_u32_e32 v81, s14, v144
	v_add_u32_e32 v139, s14, v159
	v_add_u32_e32 v82, s14, v157
	ds_read_b128 v[96:99], v81
	ds_read_b128 v[100:103], v82
	v_add_u32_e32 v141, s14, v160
	ds_read_b128 v[104:107], v139
	ds_read_b128 v[108:111], v141
	v_or_b32_e32 v80, 0x4000, v166
	v_add_u32_e32 v142, v162, v80
	v_add_u32_e32 v140, v163, v80
	v_add_u32_e32 v138, v164, v80
	v_add_u32_e32 v137, v165, v80
	ds_read_b128 v[162:165], v81 offset:4096
	ds_read_b128 v[166:169], v82 offset:4096
	s_waitcnt lgkmcnt(5)
	v_mfma_f32_32x32x16_bf16 v[80:95], v[96:99], v[124:127], v[0:15]
	v_cvt_pk_bf16_f32 v128, v194, v195
	v_cvt_pk_bf16_f32 v129, v196, v197
	v_cvt_pk_bf16_f32 v130, v198, v200
	v_cvt_pk_bf16_f32 v131, v199, v201
	s_waitcnt lgkmcnt(4)
	v_mfma_f32_32x32x16_bf16 v[80:95], v[100:103], v[120:123], v[80:95]
	ds_read_b128 v[202:205], v139 offset:4096
	ds_read_b128 v[206:209], v141 offset:4096
	v_cvt_pk_bf16_f32 v132, v180, v181
	v_cvt_pk_bf16_f32 v133, v182, v183
	v_cvt_pk_bf16_f32 v134, v193, v189
	v_cvt_pk_bf16_f32 v135, v190, v192
	s_waitcnt lgkmcnt(5)
	v_mfma_f32_32x32x16_bf16 v[80:95], v[104:107], v[116:119], v[80:95]
	s_add_i32 s15, 0, 0x10000
	v_add_u32_e32 v139, s15, v142
	v_add_u32_e32 v141, s15, v140
	ds_read_b128 v[214:217], v139
	ds_read_b128 v[218:221], v141
	v_cvt_pk_bf16_f32 v210, v173, v174
	v_cvt_pk_bf16_f32 v211, v175, v176
	v_cvt_pk_bf16_f32 v212, v191, v188
	v_cvt_pk_bf16_f32 v213, v171, v172
	s_waitcnt lgkmcnt(6)
	v_mfma_f32_32x32x16_bf16 v[80:95], v[108:111], v[112:115], v[80:95]
	v_add_u32_e32 v143, s15, v138
	v_add_u32_e32 v144, s15, v137
	ds_read_b128 v[226:229], v143
	ds_read_b128 v[230:233], v144
	v_cvt_pk_bf16_f32 v222, v185, v186
	v_cvt_pk_bf16_f32 v223, v187, v184
	v_cvt_pk_bf16_f32 v224, v177, v178
	v_cvt_pk_bf16_f32 v225, v179, v161
	v_add_f32_e32 v96, 0, v194
	v_add_f32_e32 v96, v195, v96
	v_add_f32_e32 v96, v196, v96
	v_add_f32_e32 v96, v197, v96
	v_add_f32_e32 v96, v198, v96
	v_add_f32_e32 v157, v200, v96
	s_waitcnt lgkmcnt(7)
	v_mfma_f32_32x32x16_bf16 v[96:111], v[162:165], v[124:127], v[0:15]
	v_add_f32_e32 v124, v199, v157
	v_add_f32_e32 v124, v201, v124
	s_waitcnt lgkmcnt(6)
	v_mfma_f32_32x32x16_bf16 v[96:111], v[166:169], v[120:123], v[96:111]
	v_exp_f32_e32 v125, v80
	v_exp_f32_e32 v126, v81
	v_exp_f32_e32 v127, v82
	v_exp_f32_e32 v157, v83
	s_waitcnt lgkmcnt(5)
	v_mfma_f32_32x32x16_bf16 v[96:111], v[202:205], v[116:119], v[96:111]
	v_exp_f32_e32 v122, v84
	v_exp_f32_e32 v123, v85
	v_exp_f32_e32 v159, v86
	v_exp_f32_e32 v160, v87
	s_waitcnt lgkmcnt(4)
	v_mfma_f32_32x32x16_bf16 v[96:111], v[206:209], v[112:115], v[96:111]
	v_exp_f32_e32 v162, v88
	v_exp_f32_e32 v163, v89
	v_exp_f32_e32 v164, v90
	v_exp_f32_e32 v165, v91
	s_waitcnt lgkmcnt(3)
	v_mfma_f32_32x32x16_bf16 v[64:79], v[128:131], v[214:217], v[64:79]
	ds_read_b128 v[80:83], v139 offset:4096
	v_exp_f32_e32 v166, v92
	v_exp_f32_e32 v167, v93
	v_exp_f32_e32 v168, v94
	v_exp_f32_e32 v169, v95
	s_waitcnt lgkmcnt(3)
	v_mfma_f32_32x32x16_bf16 v[64:79], v[132:135], v[218:221], v[64:79]
	v_add_f32_e32 v88, v180, v124
	v_add_f32_e32 v88, v181, v88
	ds_read_b128 v[84:87], v141 offset:4096
	v_add_f32_e32 v88, v182, v88
	v_add_f32_e32 v88, v183, v88
	v_add_f32_e32 v88, v193, v88
	v_add_f32_e32 v88, v189, v88
	v_add_f32_e32 v88, v190, v88
	v_add_f32_e32 v112, v192, v88
	s_waitcnt lgkmcnt(3)
	v_mfma_f32_32x32x16_bf16 v[64:79], v[210:213], v[226:229], v[64:79]
	ds_read_b128 v[88:91], v143 offset:4096
	v_exp_f32_e32 v124, v96
	v_exp_f32_e32 v170, v97
	v_exp_f32_e32 v180, v98
	v_exp_f32_e32 v181, v99
	s_waitcnt lgkmcnt(3)
	v_mfma_f32_32x32x16_bf16 v[64:79], v[222:225], v[230:233], v[64:79]
	ds_read_b128 v[92:95], v144 offset:4096
	v_add_f32_e32 v96, v173, v112
	v_add_f32_e32 v96, v174, v96
	v_add_f32_e32 v96, v175, v96
	v_add_f32_e32 v96, v176, v96
	v_add_f32_e32 v96, v191, v96
	v_add_f32_e32 v112, v188, v96
	s_waitcnt lgkmcnt(3)
	v_mfma_f32_32x32x16_bf16 v[48:63], v[128:131], v[80:83], v[48:63]
	ds_read_b128 v[96:99], v139 offset:8192
	v_exp_f32_e32 v173, v100
	v_exp_f32_e32 v174, v101
	v_exp_f32_e32 v175, v102
	v_exp_f32_e32 v176, v103
	s_waitcnt lgkmcnt(3)
	v_mfma_f32_32x32x16_bf16 v[48:63], v[132:135], v[84:87], v[48:63]
	ds_read_b128 v[80:83], v141 offset:8192
	v_add_f32_e32 v100, v171, v112
	v_add_f32_e32 v100, v172, v100
	v_add_f32_e32 v100, v185, v100
	v_add_f32_e32 v100, v186, v100
	v_add_f32_e32 v100, v187, v100
	v_add_f32_e32 v100, v184, v100
	s_waitcnt lgkmcnt(3)
	v_mfma_f32_32x32x16_bf16 v[48:63], v[210:213], v[88:91], v[48:63]
	ds_read_b128 v[84:87], v143 offset:8192
	v_exp_f32_e32 v171, v104
	v_exp_f32_e32 v172, v105
	v_exp_f32_e32 v182, v106
	v_exp_f32_e32 v183, v107
	s_waitcnt lgkmcnt(3)
	v_mfma_f32_32x32x16_bf16 v[48:63], v[222:225], v[92:95], v[48:63]
	ds_read_b128 v[88:91], v144 offset:8192
	v_add_f32_e32 v100, v177, v100
	v_add_f32_e32 v100, v178, v100
	v_add_f32_e32 v177, v179, v100
	s_waitcnt lgkmcnt(3)
	v_mfma_f32_32x32x16_bf16 v[32:47], v[128:131], v[96:99], v[32:47]
	ds_read_b128 v[92:95], v139 offset:12288
	v_exp_f32_e32 v178, v108
	v_exp_f32_e32 v179, v109
	v_exp_f32_e32 v184, v110
	v_exp_f32_e32 v185, v111
	s_waitcnt lgkmcnt(3)
	v_mfma_f32_32x32x16_bf16 v[32:47], v[132:135], v[80:83], v[32:47]
	ds_read_b128 v[96:99], v141 offset:12288
	s_waitcnt lgkmcnt(3)
	v_mfma_f32_32x32x16_bf16 v[32:47], v[210:213], v[84:87], v[32:47]
	ds_read_b128 v[80:83], v143 offset:12288
	s_waitcnt lgkmcnt(3)
	v_mfma_f32_32x32x16_bf16 v[32:47], v[222:225], v[88:91], v[32:47]
	ds_read_b128 v[84:87], v144 offset:12288
	s_waitcnt lgkmcnt(3)
	v_mfma_f32_32x32x16_bf16 v[16:31], v[128:131], v[92:95], v[16:31]
	s_add_u32 s12, s12, 0x230000
	s_addc_u32 s13, s13, 0
	s_mov_b32 m0, s71
	s_nop 0
	global_load_lds_dwordx4 v156, s[12:13]
	s_waitcnt lgkmcnt(2)
	v_mfma_f32_32x32x16_bf16 v[16:31], v[132:135], v[96:99], v[16:31]
	s_mov_b32 m0, s72
	s_nop 0
	global_load_lds_dwordx4 v154, s[12:13]
	s_waitcnt lgkmcnt(1)
	v_mfma_f32_32x32x16_bf16 v[16:31], v[210:213], v[80:83], v[16:31]
	s_add_u32 s10, s10, 0x1180
	s_addc_u32 s11, s11, 0
	s_mov_b32 m0, s73
	s_nop 0
	global_load_lds_dwordx4 v150, s[10:11]
	s_waitcnt lgkmcnt(0)
	v_mfma_f32_32x32x16_bf16 v[16:31], v[222:225], v[84:87], v[16:31]
	s_mov_b32 m0, s78
	s_nop 0
	global_load_lds_dwordx4 v148, s[10:11]
	v_add_u32_e32 v80, s14, v142
	v_cvt_pk_bf16_f32 v98, v125, v126
	v_cvt_pk_bf16_f32 v99, v127, v157
	v_cvt_pk_bf16_f32 v100, v122, v123
	v_cvt_pk_bf16_f32 v101, v159, v160
	ds_read_b128 v[80:83], v80
	v_add_u32_e32 v84, s14, v140
	ds_read_b128 v[84:87], v84
	s_waitcnt lgkmcnt(1)
	v_mfma_f32_32x32x16_bf16 v[64:79], v[98:101], v[80:83], v[64:79]
	v_cvt_pk_bf16_f32 v102, v162, v163
	v_cvt_pk_bf16_f32 v103, v164, v165
	v_cvt_pk_bf16_f32 v104, v166, v167
	v_cvt_pk_bf16_f32 v105, v168, v169
	v_add_u32_e32 v80, s14, v138
	v_cvt_pk_bf16_f32 v106, v124, v170
	v_cvt_pk_bf16_f32 v107, v180, v181
	s_waitcnt lgkmcnt(0)
	v_mfma_f32_32x32x16_bf16 v[64:79], v[102:105], v[84:87], v[64:79]
	v_cvt_pk_bf16_f32 v108, v173, v174
	v_cvt_pk_bf16_f32 v109, v175, v176
	ds_read_b128 v[80:83], v80
	v_add_u32_e32 v84, s14, v137
	ds_read_b128 v[84:87], v84
	v_cvt_pk_bf16_f32 v110, v171, v172
	v_cvt_pk_bf16_f32 v111, v182, v183
	s_waitcnt lgkmcnt(1)
	v_mfma_f32_32x32x16_bf16 v[64:79], v[106:109], v[80:83], v[64:79]
	v_cvt_pk_bf16_f32 v112, v178, v179
	v_cvt_pk_bf16_f32 v113, v184, v185
	v_add_u32_e32 v80, s91, v142
	ds_read_b128 v[80:83], v80
	v_ashrrev_i32_e32 v88, 4, v146
	v_add_u32_e32 v139, s69, v88
	s_lshl_b32 s10, s60, 1
	s_waitcnt lgkmcnt(1)
	v_mfma_f32_32x32x16_bf16 v[64:79], v[110:113], v[84:87], v[64:79]
	v_add_u32_e32 v84, s91, v140
	ds_read_b128 v[84:87], v84
	v_add_u32_e32 v96, s59, v139
	s_add_u32 s4, s4, s10
	s_addc_u32 s5, s5, 0
	v_ashrrev_i32_e32 v97, 31, v96
	v_add_u32_e32 v118, s92, v140
	s_waitcnt lgkmcnt(1)
	v_mfma_f32_32x32x16_bf16 v[48:63], v[98:101], v[80:83], v[48:63]
	v_lshlrev_b32_e32 v80, 3, v146
	v_and_b32_e32 v143, 0x78, v80
	v_add_u32_e32 v80, s91, v138
	ds_read_b128 v[80:83], v80
	v_lshlrev_b32_e32 v144, 1, v143
	v_lshl_add_u64 v[88:89], s[4:5], 0, v[144:145]
	s_mov_b32 s4, 0x9c01000
	s_waitcnt lgkmcnt(1)
	v_mfma_f32_32x32x16_bf16 v[48:63], v[102:105], v[84:87], v[48:63]
	v_lshlrev_b64 v[84:85], 10, v[96:97]
	v_lshl_add_u64 v[114:115], v[88:89], 0, v[84:85]
	v_add_u32_e32 v84, s91, v137
	ds_read_b128 v[84:87], v84
	v_add_f32_e32 v125, 0, v125
	s_waitcnt lgkmcnt(1)
	v_mfma_f32_32x32x16_bf16 v[48:63], v[106:109], v[80:83], v[48:63]
	v_add_co_u32_e64 v80, s[4:5], s4, v114
	s_nop 1
	v_addc_co_u32_e64 v81, s[4:5], 0, v115, s[4:5]
	s_mov_b32 s4, 0x9c03000
	global_load_dwordx4 v[92:95], v[80:81], off offset:-4096
	global_load_dwordx4 v[88:91], v[80:81], off
	v_add_co_u32_e64 v80, s[4:5], s4, v114
	s_waitcnt lgkmcnt(0)
	v_mfma_f32_32x32x16_bf16 v[48:63], v[110:113], v[84:87], v[48:63]
	v_addc_co_u32_e64 v81, s[4:5], 0, v115, s[4:5]
	global_load_dwordx4 v[84:87], v[80:81], off offset:-4096
	s_nop 0
	global_load_dwordx4 v[80:83], v[80:81], off
	v_add_u32_e32 v114, s92, v142
	ds_read_b128 v[114:117], v114
	ds_read_b128 v[118:121], v118
	s_waitcnt lgkmcnt(1)
	v_mfma_f32_32x32x16_bf16 v[32:47], v[98:101], v[114:117], v[32:47]
	v_add_f32_e32 v114, 0, v124
	v_add_f32_e32 v115, v126, v125
	v_add_f32_e32 v114, v170, v114
	v_add_f32_e32 v115, v127, v115
	v_add_f32_e32 v114, v180, v114
	v_add_f32_e32 v115, v157, v115
	v_add_f32_e32 v124, v181, v114
	s_waitcnt lgkmcnt(0)
	v_mfma_f32_32x32x16_bf16 v[32:47], v[102:105], v[118:121], v[32:47]
	v_add_u32_e32 v114, s92, v138
	v_add_f32_e32 v118, v122, v115
	ds_read_b128 v[114:117], v114
	v_add_f32_e32 v123, v123, v118
	v_add_u32_e32 v118, s92, v137
	ds_read_b128 v[118:121], v118
	v_add_f32_e32 v122, v173, v124
	s_waitcnt lgkmcnt(1)
	v_mfma_f32_32x32x16_bf16 v[32:47], v[106:109], v[114:117], v[32:47]
	v_add_f32_e32 v114, v174, v122
	v_add_f32_e32 v115, v159, v123
	v_add_f32_e32 v114, v175, v114
	v_add_f32_e32 v115, v160, v115
	v_add_f32_e32 v114, v176, v114
	v_add_f32_e32 v115, v162, v115
	v_add_f32_e32 v122, v171, v114
	v_add_u32_e32 v114, s93, v142
	s_waitcnt lgkmcnt(0)
	v_mfma_f32_32x32x16_bf16 v[32:47], v[110:113], v[118:121], v[32:47]
	v_add_f32_e32 v118, v163, v115
	ds_read_b128 v[114:117], v114
	v_add_f32_e32 v123, v164, v118
	v_add_u32_e32 v118, s93, v140
	ds_read_b128 v[118:121], v118
	v_add_f32_e32 v122, v172, v122
	s_waitcnt lgkmcnt(1)
	v_mfma_f32_32x32x16_bf16 v[16:31], v[98:101], v[114:117], v[16:31]
	v_add_f32_e32 v98, v182, v122
	v_add_f32_e32 v99, v165, v123
	v_add_f32_e32 v98, v183, v98
	v_add_f32_e32 v99, v166, v99
	v_add_f32_e32 v98, v178, v98
	v_add_f32_e32 v99, v167, v99
	v_add_f32_e32 v114, v179, v98
	s_waitcnt lgkmcnt(0)
	v_mfma_f32_32x32x16_bf16 v[16:31], v[102:105], v[118:121], v[16:31]
	v_add_u32_e32 v98, s93, v138
	v_add_f32_e32 v102, v168, v99
	ds_read_b128 v[98:101], v98
	v_add_f32_e32 v115, v169, v102
	v_add_u32_e32 v102, s93, v137
	ds_read_b128 v[102:105], v102
	v_add_f32_e32 v114, v184, v114
	s_waitcnt lgkmcnt(1)
	v_mfma_f32_32x32x16_bf16 v[16:31], v[106:109], v[98:101], v[16:31]
	v_add_f32_e32 v98, v185, v114
	v_add_f32_e32 v99, v161, v177
	v_add_f32_e32 v98, v115, v98
	v_add_f32_e32 v99, v158, v99
	v_lshlrev_b32_e32 v115, 2, v146
	v_add_f32_e32 v98, v99, v98
	v_xor_b32_e32 v99, 0x80, v115
	s_waitcnt lgkmcnt(0)
	v_mfma_f32_32x32x16_bf16 v[16:31], v[110:113], v[102:105], v[16:31]
	ds_bpermute_b32 v99, v99, v98
	s_waitcnt vmcnt(0) lgkmcnt(0)
	s_barrier
	s_and_saveexec_b64 s[4:5], vcc
	s_cbranch_execz .LBB0_654
	v_mov_b32_e32 v100, s89
	ds_write_b32 v100, v136
